# speedup vs baseline: 1.0061x; 1.0052x over previous
;     __device__ __forceinline__ const char* a_base(const Gemm& g, const Unit& u, size_t tstepA) const { return (const char*)g.A + (size_t)u.pm * tstepA; }
;     __device__ __forceinline__ const char* b_base(const Gemm& g, const Unit& u, size_t tstepB) const { return (const char*)g.Bt + (size_t)u.pn * tstepB; }
;     __device__ __forceinline__ bool next(int i, Unit& u) const { const int ti = i / 3; if (!StaticOrder::next(ti, u)) return false; u.s = i - 3 * ti; return true; }
; template <class Epi, class Sched, bool ALIGN_EPI = false, bool SP2 = false, bool FP8 = false>
; __device__ __forceinline__ void gemm_phase(PG8_LAS unsigned char* lds, const Gemm g, const Sched& S, const Epi& E, const int tid) {
;     ...
;         const bool has_next = S.next(ui + 1, nxt);
;         const char* nA = has_next ? S.a_base(g, nxt, tstepA) : cA; const char* nB = has_next ? S.b_base(g, nxt, tstepB) : cB;
;     ...
;         if (S.fresh(nxt)) {
; #pragma unroll
;         for (int a = 0; a < 2; ++a)
; #pragma unroll
;             for (int b = 0; b < 2; ++b)
; #pragma unroll
;                 for (int m = 0; m < 4; ++m)
; #pragma unroll
;                     for (int n = 0; n < 2; ++n) acc[a][b][m][n] = (f32x4){0.f, 0.f, 0.f, 0.f};
;         }
.LBB0_97:
	s_ashr_i32 s27, s26, 31
	s_lshl_b64 s[28:29], s[26:27], 20
	s_add_u32 s28, s0, s28
	s_addc_u32 s29, s20, s29
	s_and_b64 s[30:31], s[4:5], exec
	s_cselect_b32 s27, s29, s35
	s_cselect_b32 s52, s28, s34
	s_ashr_i32 s25, s24, 31
	s_lshl_b64 s[30:31], s[24:25], 20
	s_add_u32 s30, s22, s30
	s_addc_u32 s31, s33, s31
	s_and_b64 s[40:41], s[4:5], exec
	s_cselect_b32 s25, s31, s37
	s_cselect_b32 s53, s30, s36
	s_add_u32 s34, s34, 0x80080
	s_addc_u32 s35, s35, 0
	s_add_u32 s54, s36, 0x100
	v_mov_b32_e32 v0, 0
	s_addc_u32 s55, s37, 0
	s_mov_b32 s56, -2
	v_mov_b32_e32 v1, v0
	v_mov_b32_e32 v2, v0
	v_mov_b32_e32 v3, v0
	v_mov_b32_e32 v4, v0
	v_mov_b32_e32 v5, v0
	v_mov_b32_e32 v6, v0
	v_mov_b32_e32 v7, v0
	v_mov_b32_e32 v16, v0
	v_mov_b32_e32 v17, v0
	v_mov_b32_e32 v18, v0
	v_mov_b32_e32 v19, v0
	v_mov_b32_e32 v20, v0
	v_mov_b32_e32 v21, v0
	v_mov_b32_e32 v22, v0
	v_mov_b32_e32 v23, v0
	v_mov_b32_e32 v34, v0
	v_mov_b32_e32 v35, v0
	v_mov_b32_e32 v36, v0
	v_mov_b32_e32 v37, v0
	v_mov_b32_e32 v38, v0
	v_mov_b32_e32 v39, v0
	v_mov_b32_e32 v40, v0
	v_mov_b32_e32 v41, v0
	v_mov_b32_e32 v50, v0
	v_mov_b32_e32 v51, v0
	v_mov_b32_e32 v52, v0
	v_mov_b32_e32 v53, v0
	v_mov_b32_e32 v54, v0
	v_mov_b32_e32 v55, v0
	v_mov_b32_e32 v56, v0
	v_mov_b32_e32 v57, v0
	v_mov_b32_e32 v8, v0
	v_mov_b32_e32 v9, v0
	v_mov_b32_e32 v10, v0
	v_mov_b32_e32 v11, v0
	v_mov_b32_e32 v12, v0
	v_mov_b32_e32 v13, v0
	v_mov_b32_e32 v14, v0
	v_mov_b32_e32 v15, v0
	v_mov_b32_e32 v24, v0
	v_mov_b32_e32 v25, v0
	v_mov_b32_e32 v26, v0
	v_mov_b32_e32 v27, v0
	v_mov_b32_e32 v28, v0
	v_mov_b32_e32 v29, v0
	v_mov_b32_e32 v30, v0
	v_mov_b32_e32 v31, v0
	v_mov_b32_e32 v42, v0
	v_mov_b32_e32 v43, v0
	v_mov_b32_e32 v44, v0
	v_mov_b32_e32 v45, v0
	v_mov_b32_e32 v46, v0
	v_mov_b32_e32 v47, v0
	v_mov_b32_e32 v48, v0
	v_mov_b32_e32 v49, v0
	v_mov_b32_e32 v58, v0
	v_mov_b32_e32 v59, v0
	v_mov_b32_e32 v60, v0
	v_mov_b32_e32 v61, v0
	v_mov_b32_e32 v62, v0
	v_mov_b32_e32 v63, v0
	v_mov_b32_e32 v64, v0
	v_mov_b32_e32 v65, v0
	v_mov_b32_e32 v66, v0
	v_mov_b32_e32 v67, v0
	v_mov_b32_e32 v68, v0
	v_mov_b32_e32 v69, v0
	v_mov_b32_e32 v70, v0
	v_mov_b32_e32 v71, v0
	v_mov_b32_e32 v72, v0
	v_mov_b32_e32 v73, v0
	v_mov_b32_e32 v82, v0
	v_mov_b32_e32 v83, v0
	v_mov_b32_e32 v84, v0
	v_mov_b32_e32 v85, v0
	v_mov_b32_e32 v86, v0
	v_mov_b32_e32 v87, v0
	v_mov_b32_e32 v88, v0
	v_mov_b32_e32 v89, v0
	v_mov_b32_e32 v98, v0
	v_mov_b32_e32 v99, v0
	v_mov_b32_e32 v100, v0
	v_mov_b32_e32 v101, v0
	v_mov_b32_e32 v102, v0
	v_mov_b32_e32 v103, v0
	v_mov_b32_e32 v104, v0
	v_mov_b32_e32 v105, v0
	v_mov_b32_e32 v114, v0
	v_mov_b32_e32 v115, v0
	v_mov_b32_e32 v116, v0
	v_mov_b32_e32 v117, v0
	v_mov_b32_e32 v118, v0
	v_mov_b32_e32 v119, v0
	v_mov_b32_e32 v120, v0
	v_mov_b32_e32 v121, v0
	v_mov_b32_e32 v74, v0
	v_mov_b32_e32 v75, v0
	v_mov_b32_e32 v76, v0
	v_mov_b32_e32 v77, v0
	v_mov_b32_e32 v78, v0
	v_mov_b32_e32 v79, v0
	v_mov_b32_e32 v80, v0
	v_mov_b32_e32 v81, v0
	v_mov_b32_e32 v90, v0
	v_mov_b32_e32 v91, v0
	v_mov_b32_e32 v92, v0
	v_mov_b32_e32 v93, v0
	v_mov_b32_e32 v94, v0
	v_mov_b32_e32 v95, v0
	v_mov_b32_e32 v96, v0
	v_mov_b32_e32 v97, v0
	v_mov_b32_e32 v106, v0
	v_mov_b32_e32 v107, v0
	v_mov_b32_e32 v108, v0
	v_mov_b32_e32 v109, v0
	v_mov_b32_e32 v110, v0
	v_mov_b32_e32 v111, v0
	v_mov_b32_e32 v112, v0
	v_mov_b32_e32 v113, v0
	v_mov_b32_e32 v122, v0
	v_mov_b32_e32 v123, v0
	v_mov_b32_e32 v124, v0
	v_mov_b32_e32 v125, v0
	v_mov_b32_e32 v126, v0
	v_mov_b32_e32 v127, v0
	v_mov_b32_e32 v128, v0
	v_mov_b32_e32 v129, v0
	v_readfirstlane_b32 vcc_lo, v202
	s_bitcmp1_b32 vcc_lo, 8
	s_cbranch_scc1 .Lsprio_98
	s_setprio 1

;     __device__ __forceinline__ const char* a_base(const Gemm& g, const Unit& u, size_t tstepA) const { return (const char*)g.A + (size_t)u.pm * tstepA; }
;     __device__ __forceinline__ const char* b_base(const Gemm& g, const Unit& u, size_t tstepB) const { return (const char*)g.Bt + (size_t)u.pn * tstepB; }
;     __device__ __forceinline__ bool next(int i, Unit& u) const { const int ti = i / 3; if (!StaticOrder::next(ti, u)) return false; u.s = i - 3 * ti; return true; }
; template <class Epi, class Sched, bool ALIGN_EPI = false, bool SP2 = false, bool FP8 = false>
; __device__ __forceinline__ void gemm_phase(PG8_LAS unsigned char* lds, const Gemm g, const Sched& S, const Epi& E, const int tid) {
;     ...
;         const bool has_next = S.next(ui + 1, nxt);
;         const char* nA = has_next ? S.a_base(g, nxt, tstepA) : cA; const char* nB = has_next ? S.b_base(g, nxt, tstepB) : cB;
;     ...
;         if (S.fresh(nxt)) {
; #pragma unroll
;         for (int a = 0; a < 2; ++a)
; #pragma unroll
;             for (int b = 0; b < 2; ++b)
; #pragma unroll
;                 for (int m = 0; m < 4; ++m)
; #pragma unroll
;                     for (int n = 0; n < 2; ++n) acc[a][b][m][n] = (f32x4){0.f, 0.f, 0.f, 0.f};
;         }
.LBB0_113:
	s_ashr_i32 s25, s24, 31
	s_lshl_b64 s[26:27], s[24:25], 19
	s_add_u32 s26, s40, s26
	s_addc_u32 s27, s41, s27
	s_and_b64 s[28:29], s[4:5], exec
	s_cselect_b32 s22, s27, s31
	s_cselect_b32 s25, s26, s30
	s_ashr_i32 s17, s16, 31
	s_lshl_b64 s[28:29], s[16:17], 19
	s_add_u32 s28, s42, s28
	s_addc_u32 s29, s43, s29
	s_and_b64 s[36:37], s[4:5], exec
	s_cselect_b32 s17, s29, s35
	s_cselect_b32 s33, s28, s34
	s_add_u32 s30, s30, 0x40080
	s_addc_u32 s31, s31, 0
	s_add_u32 s52, s34, 0x100
	v_mov_b32_e32 v34, 0
	s_addc_u32 s53, s35, 0
	s_mov_b32 s54, -2
	v_mov_b32_e32 v35, v34
	v_mov_b32_e32 v36, v34
	v_mov_b32_e32 v37, v34
	v_mov_b32_e32 v38, v34
	v_mov_b32_e32 v39, v34
	v_mov_b32_e32 v40, v34
	v_mov_b32_e32 v41, v34
	v_mov_b32_e32 v50, v34
	v_mov_b32_e32 v51, v34
	v_mov_b32_e32 v52, v34
	v_mov_b32_e32 v53, v34
	v_mov_b32_e32 v54, v34
	v_mov_b32_e32 v55, v34
	v_mov_b32_e32 v56, v34
	v_mov_b32_e32 v57, v34
	v_mov_b32_e32 v66, v34
	v_mov_b32_e32 v67, v34
	v_mov_b32_e32 v68, v34
	v_mov_b32_e32 v69, v34
	v_mov_b32_e32 v70, v34
	v_mov_b32_e32 v71, v34
	v_mov_b32_e32 v72, v34
	v_mov_b32_e32 v73, v34
	v_mov_b32_e32 v82, v34
	v_mov_b32_e32 v83, v34
	v_mov_b32_e32 v84, v34
	v_mov_b32_e32 v85, v34
	v_mov_b32_e32 v86, v34
	v_mov_b32_e32 v87, v34
	v_mov_b32_e32 v88, v34
	v_mov_b32_e32 v89, v34
	v_mov_b32_e32 v42, v34
	v_mov_b32_e32 v43, v34
	v_mov_b32_e32 v44, v34
	v_mov_b32_e32 v45, v34
	v_mov_b32_e32 v46, v34
	v_mov_b32_e32 v47, v34
	v_mov_b32_e32 v48, v34
	v_mov_b32_e32 v49, v34
	v_mov_b32_e32 v58, v34
	v_mov_b32_e32 v59, v34
	v_mov_b32_e32 v60, v34
	v_mov_b32_e32 v61, v34
	v_mov_b32_e32 v62, v34
	v_mov_b32_e32 v63, v34
	v_mov_b32_e32 v64, v34
	v_mov_b32_e32 v65, v34
	v_mov_b32_e32 v74, v34
	v_mov_b32_e32 v75, v34
	v_mov_b32_e32 v76, v34
	v_mov_b32_e32 v77, v34
	v_mov_b32_e32 v78, v34
	v_mov_b32_e32 v79, v34
	v_mov_b32_e32 v80, v34
	v_mov_b32_e32 v81, v34
	v_mov_b32_e32 v90, v34
	v_mov_b32_e32 v91, v34
	v_mov_b32_e32 v92, v34
	v_mov_b32_e32 v93, v34
	v_mov_b32_e32 v94, v34
	v_mov_b32_e32 v95, v34
	v_mov_b32_e32 v96, v34
	v_mov_b32_e32 v97, v34
	v_mov_b32_e32 v98, v34
	v_mov_b32_e32 v99, v34
	v_mov_b32_e32 v100, v34
	v_mov_b32_e32 v101, v34
	v_mov_b32_e32 v102, v34
	v_mov_b32_e32 v103, v34
	v_mov_b32_e32 v104, v34
	v_mov_b32_e32 v105, v34
	v_mov_b32_e32 v114, v34
	v_mov_b32_e32 v115, v34
	v_mov_b32_e32 v116, v34
	v_mov_b32_e32 v117, v34
	v_mov_b32_e32 v118, v34
	v_mov_b32_e32 v119, v34
	v_mov_b32_e32 v120, v34
	v_mov_b32_e32 v121, v34
	v_mov_b32_e32 v130, v34
	v_mov_b32_e32 v131, v34
	v_mov_b32_e32 v132, v34
	v_mov_b32_e32 v133, v34
	v_mov_b32_e32 v134, v34
	v_mov_b32_e32 v135, v34
	v_mov_b32_e32 v136, v34
	v_mov_b32_e32 v137, v34
	v_mov_b32_e32 v146, v34
	v_mov_b32_e32 v147, v34
	v_mov_b32_e32 v148, v34
	v_mov_b32_e32 v149, v34
	v_mov_b32_e32 v150, v34
	v_mov_b32_e32 v151, v34
	v_mov_b32_e32 v152, v34
	v_mov_b32_e32 v153, v34
	v_mov_b32_e32 v106, v34
	v_mov_b32_e32 v107, v34
	v_mov_b32_e32 v108, v34
	v_mov_b32_e32 v109, v34
	v_mov_b32_e32 v110, v34
	v_mov_b32_e32 v111, v34
	v_mov_b32_e32 v112, v34
	v_mov_b32_e32 v113, v34
	v_mov_b32_e32 v122, v34
	v_mov_b32_e32 v123, v34
	v_mov_b32_e32 v124, v34
	v_mov_b32_e32 v125, v34
	v_mov_b32_e32 v126, v34
	v_mov_b32_e32 v127, v34
	v_mov_b32_e32 v128, v34
	v_mov_b32_e32 v129, v34
	v_mov_b32_e32 v138, v34
	v_mov_b32_e32 v139, v34
	v_mov_b32_e32 v140, v34
	v_mov_b32_e32 v141, v34
	v_mov_b32_e32 v142, v34
	v_mov_b32_e32 v143, v34
	v_mov_b32_e32 v144, v34
	v_mov_b32_e32 v145, v34
	v_mov_b32_e32 v154, v34
	v_mov_b32_e32 v155, v34
	v_mov_b32_e32 v156, v34
	v_mov_b32_e32 v157, v34
	v_mov_b32_e32 v158, v34
	v_mov_b32_e32 v159, v34
	v_mov_b32_e32 v160, v34
	v_mov_b32_e32 v161, v34
	v_readfirstlane_b32 vcc_lo, v202
	s_bitcmp1_b32 vcc_lo, 8
	s_cbranch_scc1 .Lsprio_114
	s_setprio 1

;     __device__ __forceinline__ const char* a_base(const Gemm& g, const Unit& u, size_t tstepA) const { return (const char*)g.A + (size_t)u.pm * tstepA; }
;     __device__ __forceinline__ const char* b_base(const Gemm& g, const Unit& u, size_t tstepB) const { return (const char*)g.Bt + (size_t)u.pn * tstepB; }
;     __device__ __forceinline__ bool next(int i, Unit& u) const { const int ti = i / 3; if (!StaticOrder::next(ti, u)) return false; u.s = i - 3 * ti; return true; }
; template <class Epi, class Sched, bool ALIGN_EPI = false, bool SP2 = false, bool FP8 = false>
; __device__ __forceinline__ void gemm_phase(PG8_LAS unsigned char* lds, const Gemm g, const Sched& S, const Epi& E, const int tid) {
;     ...
;         const bool has_next = S.next(ui + 1, nxt);
;         const char* nA = has_next ? S.a_base(g, nxt, tstepA) : cA; const char* nB = has_next ? S.b_base(g, nxt, tstepB) : cB;
;         const int nt = S.ktiles(g, cur);
;         for (int t = 0; t < nt; t += 2) {
;             const bool last = (t == nt - 2);
.LBB0_456:
	s_cmp_eq_u32 s20, 0
	s_cselect_b64 s[10:11], -1, 0
	s_and_b64 s[6:7], s[10:11], exec
	s_cselect_b32 s27, 6, 16
	s_add_i32 s57, s27, -2
	s_add_u32 s58, s34, 0x100
	s_mov_b32 s36, 0
	s_addc_u32 s59, s35, 0
	v_readfirstlane_b32 vcc_lo, v202
	s_bitcmp1_b32 vcc_lo, 8
	s_cbranch_scc1 .Lsprio_457
	s_setprio 1

;     __device__ __forceinline__ const char* a_base(const Gemm& g, const Unit& u, size_t tstepA) const { return (const char*)g.A + (size_t)u.pm * tstepA; }
;     __device__ __forceinline__ const char* b_base(const Gemm& g, const Unit& u, size_t tstepB) const { return (const char*)g.Bt + (size_t)u.pn * tstepB; }
;     __device__ __forceinline__ bool next(int i, Unit& u) const { const int ti = i / 3; if (!StaticOrder::next(ti, u)) return false; u.s = i - 3 * ti; return true; }
; template <class Epi, class Sched, bool ALIGN_EPI = false, bool SP2 = false, bool FP8 = false>
; __device__ __forceinline__ void gemm_phase(PG8_LAS unsigned char* lds, const Gemm g, const Sched& S, const Epi& E, const int tid) {
;     ...
;         const bool has_next = S.next(ui + 1, nxt);
;         const char* nA = has_next ? S.a_base(g, nxt, tstepA) : cA; const char* nB = has_next ? S.b_base(g, nxt, tstepB) : cB;
;     ...
;         if (S.fresh(nxt)) {
; #pragma unroll
;         for (int a = 0; a < 2; ++a)
; #pragma unroll
;             for (int b = 0; b < 2; ++b)
; #pragma unroll
;                 for (int m = 0; m < 4; ++m)
; #pragma unroll
;                     for (int n = 0; n < 2; ++n) acc[a][b][m][n] = (f32x4){0.f, 0.f, 0.f, 0.f};
;         }
.LBB0_588:
	s_ashr_i32 s35, s34, 31
	s_lshl_b64 s[36:37], s[34:35], 20
	s_add_u32 s36, s48, s36
	s_addc_u32 s37, s49, s37
	s_and_b64 s[42:43], s[6:7], exec
	s_cselect_b32 s33, s37, s9
	s_cselect_b32 s35, s36, s8
	s_ashr_i32 s31, s30, 31
	s_lshl_b64 s[42:43], s[30:31], 20
	s_add_u32 s42, s50, s42
	s_addc_u32 s43, s51, s43
	s_and_b64 s[46:47], s[6:7], exec
	s_cselect_b32 s31, s43, s45
	s_cselect_b32 s59, s42, s44
	s_add_u32 s8, s8, 0x80080
	s_addc_u32 s9, s9, 0
	s_add_u32 s60, s44, 0x100
	v_mov_b32_e32 v0, 0
	s_addc_u32 s61, s45, 0
	s_mov_b32 s62, -2
	s_waitcnt lgkmcnt(0)
	v_mov_b32_e32 v1, v0
	v_mov_b32_e32 v2, v0
	v_mov_b32_e32 v3, v0
	v_mov_b32_e32 v4, v0
	v_mov_b32_e32 v5, v0
	v_mov_b32_e32 v6, v0
	v_mov_b32_e32 v7, v0
	v_mov_b32_e32 v16, v0
	v_mov_b32_e32 v17, v0
	v_mov_b32_e32 v18, v0
	v_mov_b32_e32 v19, v0
	v_mov_b32_e32 v20, v0
	v_mov_b32_e32 v21, v0
	v_mov_b32_e32 v22, v0
	v_mov_b32_e32 v23, v0
	v_mov_b32_e32 v34, v0
	v_mov_b32_e32 v35, v0
	v_mov_b32_e32 v36, v0
	v_mov_b32_e32 v37, v0
	v_mov_b32_e32 v38, v0
	v_mov_b32_e32 v39, v0
	v_mov_b32_e32 v40, v0
	v_mov_b32_e32 v41, v0
	v_mov_b32_e32 v50, v0
	v_mov_b32_e32 v51, v0
	v_mov_b32_e32 v52, v0
	v_mov_b32_e32 v53, v0
	v_mov_b32_e32 v54, v0
	v_mov_b32_e32 v55, v0
	v_mov_b32_e32 v56, v0
	v_mov_b32_e32 v57, v0
	v_mov_b32_e32 v8, v0
	v_mov_b32_e32 v9, v0
	v_mov_b32_e32 v10, v0
	v_mov_b32_e32 v11, v0
	v_mov_b32_e32 v12, v0
	v_mov_b32_e32 v13, v0
	v_mov_b32_e32 v14, v0
	v_mov_b32_e32 v15, v0
	v_mov_b32_e32 v24, v0
	v_mov_b32_e32 v25, v0
	v_mov_b32_e32 v26, v0
	v_mov_b32_e32 v27, v0
	v_mov_b32_e32 v28, v0
	v_mov_b32_e32 v29, v0
	v_mov_b32_e32 v30, v0
	v_mov_b32_e32 v31, v0
	v_mov_b32_e32 v42, v0
	v_mov_b32_e32 v43, v0
	v_mov_b32_e32 v44, v0
	v_mov_b32_e32 v45, v0
	v_mov_b32_e32 v46, v0
	v_mov_b32_e32 v47, v0
	v_mov_b32_e32 v48, v0
	v_mov_b32_e32 v49, v0
	v_mov_b32_e32 v58, v0
	v_mov_b32_e32 v59, v0
	v_mov_b32_e32 v60, v0
	v_mov_b32_e32 v61, v0
	v_mov_b32_e32 v62, v0
	v_mov_b32_e32 v63, v0
	v_mov_b32_e32 v64, v0
	v_mov_b32_e32 v65, v0
	v_mov_b32_e32 v66, v0
	v_mov_b32_e32 v67, v0
	v_mov_b32_e32 v68, v0
	v_mov_b32_e32 v69, v0
	v_mov_b32_e32 v70, v0
	v_mov_b32_e32 v71, v0
	v_mov_b32_e32 v72, v0
	v_mov_b32_e32 v73, v0
	v_mov_b32_e32 v82, v0
	v_mov_b32_e32 v83, v0
	v_mov_b32_e32 v84, v0
	v_mov_b32_e32 v85, v0
	v_mov_b32_e32 v86, v0
	v_mov_b32_e32 v87, v0
	v_mov_b32_e32 v88, v0
	v_mov_b32_e32 v89, v0
	v_mov_b32_e32 v98, v0
	v_mov_b32_e32 v99, v0
	v_mov_b32_e32 v100, v0
	v_mov_b32_e32 v101, v0
	v_mov_b32_e32 v102, v0
	v_mov_b32_e32 v103, v0
	v_mov_b32_e32 v104, v0
	v_mov_b32_e32 v105, v0
	v_mov_b32_e32 v114, v0
	v_mov_b32_e32 v115, v0
	v_mov_b32_e32 v116, v0
	v_mov_b32_e32 v117, v0
	v_mov_b32_e32 v118, v0
	v_mov_b32_e32 v119, v0
	v_mov_b32_e32 v120, v0
	v_mov_b32_e32 v121, v0
	v_mov_b32_e32 v74, v0
	v_mov_b32_e32 v75, v0
	v_mov_b32_e32 v76, v0
	v_mov_b32_e32 v77, v0
	v_mov_b32_e32 v78, v0
	v_mov_b32_e32 v79, v0
	v_mov_b32_e32 v80, v0
	v_mov_b32_e32 v81, v0
	v_mov_b32_e32 v90, v0
	v_mov_b32_e32 v91, v0
	v_mov_b32_e32 v92, v0
	v_mov_b32_e32 v93, v0
	v_mov_b32_e32 v94, v0
	v_mov_b32_e32 v95, v0
	v_mov_b32_e32 v96, v0
	v_mov_b32_e32 v97, v0
	v_mov_b32_e32 v106, v0
	v_mov_b32_e32 v107, v0
	v_mov_b32_e32 v108, v0
	v_mov_b32_e32 v109, v0
	v_mov_b32_e32 v110, v0
	v_mov_b32_e32 v111, v0
	v_mov_b32_e32 v112, v0
	v_mov_b32_e32 v113, v0
	v_mov_b32_e32 v122, v0
	v_mov_b32_e32 v123, v0
	v_mov_b32_e32 v124, v0
	v_mov_b32_e32 v125, v0
	v_mov_b32_e32 v126, v0
	v_mov_b32_e32 v127, v0
	v_mov_b32_e32 v128, v0
	v_mov_b32_e32 v129, v0
	v_readfirstlane_b32 vcc_lo, v202
	s_bitcmp1_b32 vcc_lo, 8
	s_cbranch_scc1 .Lsprio_589
	s_setprio 1

;     __device__ __forceinline__ const char* a_base(const Gemm& g, const Unit& u, size_t tstepA) const { return (const char*)g.A + (size_t)u.pm * tstepA; }
;     __device__ __forceinline__ const char* b_base(const Gemm& g, const Unit& u, size_t tstepB) const { return (const char*)g.Bt + (size_t)u.pn * tstepB; }
;     __device__ __forceinline__ bool next(int i, Unit& u) const { const int ti = i / 3; if (!StaticOrder::next(ti, u)) return false; u.s = i - 3 * ti; return true; }
; template <class Epi, class Sched, bool ALIGN_EPI = false, bool SP2 = false, bool FP8 = false>
; __device__ __forceinline__ void gemm_phase(PG8_LAS unsigned char* lds, const Gemm g, const Sched& S, const Epi& E, const int tid) {
;     ...
;         const bool has_next = S.next(ui + 1, nxt);
;         const char* nA = has_next ? S.a_base(g, nxt, tstepA) : cA; const char* nB = has_next ? S.b_base(g, nxt, tstepB) : cB;
;     ...
;         if (S.fresh(nxt)) {
; #pragma unroll
;         for (int a = 0; a < 2; ++a)
; #pragma unroll
;             for (int b = 0; b < 2; ++b)
; #pragma unroll
;                 for (int m = 0; m < 4; ++m)
; #pragma unroll
;                     for (int n = 0; n < 2; ++n) acc[a][b][m][n] = (f32x4){0.f, 0.f, 0.f, 0.f};
;         }
.LBB0_734:
	s_ashr_i32 s25, s24, 31
	s_lshl_b64 s[26:27], s[24:25], 20
	s_add_u32 s26, s42, s26
	s_addc_u32 s27, s43, s27
	s_and_b64 s[28:29], s[4:5], exec
	s_cselect_b32 s25, s27, s31
	s_cselect_b32 s33, s26, s30
	s_ashr_i32 s17, s16, 31
	s_lshl_b64 s[28:29], s[16:17], 20
	s_add_u32 s28, s44, s28
	s_addc_u32 s29, s45, s29
	s_and_b64 s[36:37], s[4:5], exec
	s_cselect_b32 s17, s29, s35
	s_cselect_b32 s53, s28, s34
	s_add_u32 s30, s30, 0x80080
	s_addc_u32 s31, s31, 0
	s_add_u32 s54, s34, 0x100
	v_mov_b32_e32 v0, 0
	s_addc_u32 s55, s35, 0
	s_mov_b32 s56, -2
	v_mov_b32_e32 v1, v0
	v_mov_b32_e32 v2, v0
	v_mov_b32_e32 v3, v0
	v_mov_b32_e32 v4, v0
	v_mov_b32_e32 v5, v0
	v_mov_b32_e32 v6, v0
	v_mov_b32_e32 v7, v0
	v_mov_b32_e32 v16, v0
	v_mov_b32_e32 v17, v0
	v_mov_b32_e32 v18, v0
	v_mov_b32_e32 v19, v0
	v_mov_b32_e32 v20, v0
	v_mov_b32_e32 v21, v0
	v_mov_b32_e32 v22, v0
	v_mov_b32_e32 v23, v0
	v_mov_b32_e32 v34, v0
	v_mov_b32_e32 v35, v0
	v_mov_b32_e32 v36, v0
	v_mov_b32_e32 v37, v0
	v_mov_b32_e32 v38, v0
	v_mov_b32_e32 v39, v0
	v_mov_b32_e32 v40, v0
	v_mov_b32_e32 v41, v0
	v_mov_b32_e32 v50, v0
	v_mov_b32_e32 v51, v0
	v_mov_b32_e32 v52, v0
	v_mov_b32_e32 v53, v0
	v_mov_b32_e32 v54, v0
	v_mov_b32_e32 v55, v0
	v_mov_b32_e32 v56, v0
	v_mov_b32_e32 v57, v0
	v_mov_b32_e32 v8, v0
	v_mov_b32_e32 v9, v0
	v_mov_b32_e32 v10, v0
	v_mov_b32_e32 v11, v0
	v_mov_b32_e32 v12, v0
	v_mov_b32_e32 v13, v0
	v_mov_b32_e32 v14, v0
	v_mov_b32_e32 v15, v0
	v_mov_b32_e32 v24, v0
	v_mov_b32_e32 v25, v0
	v_mov_b32_e32 v26, v0
	v_mov_b32_e32 v27, v0
	v_mov_b32_e32 v28, v0
	v_mov_b32_e32 v29, v0
	v_mov_b32_e32 v30, v0
	v_mov_b32_e32 v31, v0
	v_mov_b32_e32 v42, v0
	v_mov_b32_e32 v43, v0
	v_mov_b32_e32 v44, v0
	v_mov_b32_e32 v45, v0
	v_mov_b32_e32 v46, v0
	v_mov_b32_e32 v47, v0
	v_mov_b32_e32 v48, v0
	v_mov_b32_e32 v49, v0
	v_mov_b32_e32 v58, v0
	v_mov_b32_e32 v59, v0
	v_mov_b32_e32 v60, v0
	v_mov_b32_e32 v61, v0
	v_mov_b32_e32 v62, v0
	v_mov_b32_e32 v63, v0
	v_mov_b32_e32 v64, v0
	v_mov_b32_e32 v65, v0
	v_mov_b32_e32 v66, v0
	v_mov_b32_e32 v67, v0
	v_mov_b32_e32 v68, v0
	v_mov_b32_e32 v69, v0
	v_mov_b32_e32 v70, v0
	v_mov_b32_e32 v71, v0
	v_mov_b32_e32 v72, v0
	v_mov_b32_e32 v73, v0
	v_mov_b32_e32 v82, v0
	v_mov_b32_e32 v83, v0
	v_mov_b32_e32 v84, v0
	v_mov_b32_e32 v85, v0
	v_mov_b32_e32 v86, v0
	v_mov_b32_e32 v87, v0
	v_mov_b32_e32 v88, v0
	v_mov_b32_e32 v89, v0
	v_mov_b32_e32 v98, v0
	v_mov_b32_e32 v99, v0
	v_mov_b32_e32 v100, v0
	v_mov_b32_e32 v101, v0
	v_mov_b32_e32 v102, v0
	v_mov_b32_e32 v103, v0
	v_mov_b32_e32 v104, v0
	v_mov_b32_e32 v105, v0
	v_mov_b32_e32 v114, v0
	v_mov_b32_e32 v115, v0
	v_mov_b32_e32 v116, v0
	v_mov_b32_e32 v117, v0
	v_mov_b32_e32 v118, v0
	v_mov_b32_e32 v119, v0
	v_mov_b32_e32 v120, v0
	v_mov_b32_e32 v121, v0
	v_mov_b32_e32 v74, v0
	v_mov_b32_e32 v75, v0
	v_mov_b32_e32 v76, v0
	v_mov_b32_e32 v77, v0
	v_mov_b32_e32 v78, v0
	v_mov_b32_e32 v79, v0
	v_mov_b32_e32 v80, v0
	v_mov_b32_e32 v81, v0
	v_mov_b32_e32 v90, v0
	v_mov_b32_e32 v91, v0
	v_mov_b32_e32 v92, v0
	v_mov_b32_e32 v93, v0
	v_mov_b32_e32 v94, v0
	v_mov_b32_e32 v95, v0
	v_mov_b32_e32 v96, v0
	v_mov_b32_e32 v97, v0
	v_mov_b32_e32 v106, v0
	v_mov_b32_e32 v107, v0
	v_mov_b32_e32 v108, v0
	v_mov_b32_e32 v109, v0
	v_mov_b32_e32 v110, v0
	v_mov_b32_e32 v111, v0
	v_mov_b32_e32 v112, v0
	v_mov_b32_e32 v113, v0
	v_mov_b32_e32 v122, v0
	v_mov_b32_e32 v123, v0
	v_mov_b32_e32 v124, v0
	v_mov_b32_e32 v125, v0
	v_mov_b32_e32 v126, v0
	v_mov_b32_e32 v127, v0
	v_mov_b32_e32 v128, v0
	v_mov_b32_e32 v129, v0
	v_readfirstlane_b32 vcc_lo, v202
	s_bitcmp1_b32 vcc_lo, 8
	s_cbranch_scc1 .Lsprio_735
	s_setprio 1

;     __device__ __forceinline__ const char* a_base(const Gemm& g, const Unit& u, size_t tstepA) const { return (const char*)g.A + (size_t)u.pm * tstepA; }
;     __device__ __forceinline__ const char* b_base(const Gemm& g, const Unit& u, size_t tstepB) const { return (const char*)g.Bt + (size_t)u.pn * tstepB; }
;     __device__ __forceinline__ bool next(int i, Unit& u) const { const int ti = i / 3; if (!StaticOrder::next(ti, u)) return false; u.s = i - 3 * ti; return true; }
; template <class Epi, class Sched, bool ALIGN_EPI = false, bool SP2 = false, bool FP8 = false>
; __device__ __forceinline__ void gemm_phase(PG8_LAS unsigned char* lds, const Gemm g, const Sched& S, const Epi& E, const int tid) {
;     ...
;         const bool has_next = S.next(ui + 1, nxt);
;         const char* nA = has_next ? S.a_base(g, nxt, tstepA) : cA; const char* nB = has_next ? S.b_base(g, nxt, tstepB) : cB;
;     ...
;         if (S.fresh(nxt)) {
; #pragma unroll
;         for (int a = 0; a < 2; ++a)
; #pragma unroll
;             for (int b = 0; b < 2; ++b)
; #pragma unroll
;                 for (int m = 0; m < 4; ++m)
; #pragma unroll
;                     for (int n = 0; n < 2; ++n) acc[a][b][m][n] = (f32x4){0.f, 0.f, 0.f, 0.f};
;         }
.LBB0_800:
	s_ashr_i32 s41, s40, 31
	s_lshl_b64 s[42:43], s[40:41], 22
	s_add_u32 s42, s0, s42
	s_addc_u32 s43, s48, s43
	s_and_b64 s[44:45], s[6:7], exec
	s_cselect_b32 s33, s43, s9
	s_cselect_b32 s41, s42, s8
	s_ashr_i32 s37, s36, 31
	s_lshl_b64 s[44:45], s[36:37], 22
	s_add_u32 s44, s49, s44
	s_addc_u32 s45, s50, s45
	s_and_b64 s[46:47], s[6:7], exec
	s_cselect_b32 s37, s45, s11
	s_cselect_b32 s59, s44, s10
	s_add_u32 s8, s8, 0x200080
	s_addc_u32 s9, s9, 0
	s_add_u32 s60, s10, 0x100
	v_mov_b32_e32 v0, 0
	s_addc_u32 s61, s11, 0
	s_mov_b32 s62, -2
	s_waitcnt lgkmcnt(0)
	v_mov_b32_e32 v1, v0
	v_mov_b32_e32 v2, v0
	v_mov_b32_e32 v3, v0
	v_mov_b32_e32 v4, v0
	v_mov_b32_e32 v5, v0
	v_mov_b32_e32 v6, v0
	v_mov_b32_e32 v7, v0
	v_mov_b32_e32 v16, v0
	v_mov_b32_e32 v17, v0
	v_mov_b32_e32 v18, v0
	v_mov_b32_e32 v19, v0
	v_mov_b32_e32 v20, v0
	v_mov_b32_e32 v21, v0
	v_mov_b32_e32 v22, v0
	v_mov_b32_e32 v23, v0
	v_mov_b32_e32 v34, v0
	v_mov_b32_e32 v35, v0
	v_mov_b32_e32 v36, v0
	v_mov_b32_e32 v37, v0
	v_mov_b32_e32 v38, v0
	v_mov_b32_e32 v39, v0
	v_mov_b32_e32 v40, v0
	v_mov_b32_e32 v41, v0
	v_mov_b32_e32 v50, v0
	v_mov_b32_e32 v51, v0
	v_mov_b32_e32 v52, v0
	v_mov_b32_e32 v53, v0
	v_mov_b32_e32 v54, v0
	v_mov_b32_e32 v55, v0
	v_mov_b32_e32 v56, v0
	v_mov_b32_e32 v57, v0
	v_mov_b32_e32 v8, v0
	v_mov_b32_e32 v9, v0
	v_mov_b32_e32 v10, v0
	v_mov_b32_e32 v11, v0
	v_mov_b32_e32 v12, v0
	v_mov_b32_e32 v13, v0
	v_mov_b32_e32 v14, v0
	v_mov_b32_e32 v15, v0
	v_mov_b32_e32 v24, v0
	v_mov_b32_e32 v25, v0
	v_mov_b32_e32 v26, v0
	v_mov_b32_e32 v27, v0
	v_mov_b32_e32 v28, v0
	v_mov_b32_e32 v29, v0
	v_mov_b32_e32 v30, v0
	v_mov_b32_e32 v31, v0
	v_mov_b32_e32 v42, v0
	v_mov_b32_e32 v43, v0
	v_mov_b32_e32 v44, v0
	v_mov_b32_e32 v45, v0
	v_mov_b32_e32 v46, v0
	v_mov_b32_e32 v47, v0
	v_mov_b32_e32 v48, v0
	v_mov_b32_e32 v49, v0
	v_mov_b32_e32 v58, v0
	v_mov_b32_e32 v59, v0
	v_mov_b32_e32 v60, v0
	v_mov_b32_e32 v61, v0
	v_mov_b32_e32 v62, v0
	v_mov_b32_e32 v63, v0
	v_mov_b32_e32 v64, v0
	v_mov_b32_e32 v65, v0
	v_mov_b32_e32 v66, v0
	v_mov_b32_e32 v67, v0
	v_mov_b32_e32 v68, v0
	v_mov_b32_e32 v69, v0
	v_mov_b32_e32 v70, v0
	v_mov_b32_e32 v71, v0
	v_mov_b32_e32 v72, v0
	v_mov_b32_e32 v73, v0
	v_mov_b32_e32 v82, v0
	v_mov_b32_e32 v83, v0
	v_mov_b32_e32 v84, v0
	v_mov_b32_e32 v85, v0
	v_mov_b32_e32 v86, v0
	v_mov_b32_e32 v87, v0
	v_mov_b32_e32 v88, v0
	v_mov_b32_e32 v89, v0
	v_mov_b32_e32 v98, v0
	v_mov_b32_e32 v99, v0
	v_mov_b32_e32 v100, v0
	v_mov_b32_e32 v101, v0
	v_mov_b32_e32 v102, v0
	v_mov_b32_e32 v103, v0
	v_mov_b32_e32 v104, v0
	v_mov_b32_e32 v105, v0
	v_mov_b32_e32 v114, v0
	v_mov_b32_e32 v115, v0
	v_mov_b32_e32 v116, v0
	v_mov_b32_e32 v117, v0
	v_mov_b32_e32 v118, v0
	v_mov_b32_e32 v119, v0
	v_mov_b32_e32 v120, v0
	v_mov_b32_e32 v121, v0
	v_mov_b32_e32 v74, v0
	v_mov_b32_e32 v75, v0
	v_mov_b32_e32 v76, v0
	v_mov_b32_e32 v77, v0
	v_mov_b32_e32 v78, v0
	v_mov_b32_e32 v79, v0
	v_mov_b32_e32 v80, v0
	v_mov_b32_e32 v81, v0
	v_mov_b32_e32 v90, v0
	v_mov_b32_e32 v91, v0
	v_mov_b32_e32 v92, v0
	v_mov_b32_e32 v93, v0
	v_mov_b32_e32 v94, v0
	v_mov_b32_e32 v95, v0
	v_mov_b32_e32 v96, v0
	v_mov_b32_e32 v97, v0
	v_mov_b32_e32 v106, v0
	v_mov_b32_e32 v107, v0
	v_mov_b32_e32 v108, v0
	v_mov_b32_e32 v109, v0
	v_mov_b32_e32 v110, v0
	v_mov_b32_e32 v111, v0
	v_mov_b32_e32 v112, v0
	v_mov_b32_e32 v113, v0
	v_mov_b32_e32 v122, v0
	v_mov_b32_e32 v123, v0
	v_mov_b32_e32 v124, v0
	v_mov_b32_e32 v125, v0
	v_mov_b32_e32 v126, v0
	v_mov_b32_e32 v127, v0
	v_mov_b32_e32 v128, v0
	v_mov_b32_e32 v129, v0
	v_readfirstlane_b32 vcc_lo, v202
	s_bitcmp1_b32 vcc_lo, 8
	s_cbranch_scc1 .Lsprio_801
	s_setprio 1
